# tile-mapping division strength-reduced to a shift at all six GEMM tile heads
# baseline (speedup 1.0000x reference)
;     __device__ bool map(long L, Unit& u) const {
;     ...
;         int wgid = (int)L; { const int q = nwg / NXCD, r = nwg % NXCD, xcd = wgid % NXCD, off = wgid / NXCD; wgid = (xcd < r ? xcd * (q + 1) : r * (q + 1) + (xcd - r) * q) + off; }
;         const int nig = WGM * nN, gid = wgid / nig, fm = gid * WGM, gsz = (nM - fm) < WGM ? (nM - fm) : WGM;
;         u.pm = fm + ((wgid % nig) % gsz); u.pn = (wgid % nig) / gsz; return true;
.LBB0_424:
	s_ashr_i32 s5, s5, 3
	s_add_i32 s5, s13, s5
	s_ashr_i32 s10, s5, 31
	s_lshr_b32 s10, s10, 27
	s_add_i32 s10, s5, s10
	s_ashr_i32 s11, s10, 5
	s_lshl_b32 s11, s11, 2
	s_sub_i32 s12, 0x80, s11
	s_min_i32 s12, s12, 4
	s_andn2_b32 s10, s10, 31
	s_sub_i32 s5, s5, s10
	s_mul_i32 s3, s3, -3
	s_ashr_i32 s13, s5, 2
	s_mul_i32 s10, s13, s12
	s_add_i32 s3, s3, s65
	s_sub_i32 s5, s5, s10
	s_lshl_b32 s3, s3, 3
	s_add_i32 s10, s11, s5
	s_add_i32 s12, s13, s3

;     __device__ bool next(int i, Unit& u) const { const int t = i / 3, b = i - 3 * t; if (!so.map((long)t * so.G + so.c, u)) return false; u.pn += 8 * b; return true; }
;     __device__ bool map(long L, Unit& u) const {
;         if (L >= nwg) return false;
;         int wgid = (int)L; { const int q = nwg / NXCD, r = nwg % NXCD, xcd = wgid % NXCD, off = wgid / NXCD; wgid = (xcd < r ? xcd * (q + 1) : r * (q + 1) + (xcd - r) * q) + off; }
;         const int nig = WGM * nN, gid = wgid / nig, fm = gid * WGM, gsz = (nM - fm) < WGM ? (nM - fm) : WGM;
;         u.pm = fm + ((wgid % nig) % gsz); u.pn = (wgid % nig) / gsz; return true;
;     }
;     __device__ bool next(int i, Unit& u) const { return map((long)i * G + c, u); }
.LBB0_616:
	s_add_i32 s41, s41, 1
	s_mul_i32 s8, s41, s36
	s_mul_hi_u32 s9, s41, s52
	s_add_i32 s9, s9, s8
	s_mul_i32 s8, s41, s52
	s_add_u32 s56, s8, s53
	s_addc_u32 s57, s9, s55
	v_mov_b64_e32 v[2:3], 0x15ff
	v_cmp_gt_i64_e64 s[8:9], s[56:57], v[2:3]
	s_and_b64 vcc, exec, s[8:9]
	s_cbranch_vccnz .LBB0_618
	s_ashr_i32 s38, s56, 31
	s_lshr_b32 s38, s38, 29
	s_add_i32 s38, s56, s38
	s_ashr_i32 s39, s38, 3
	s_and_b32 s38, s38, -8
	s_sub_i32 s38, s56, s38
	s_cmp_lt_i32 s38, 0
	s_movk_i32 s33, 0x2c1
	s_cselect_b32 s46, s33, 0x2c0
	s_mul_i32 s38, s46, s38
	s_add_i32 s38, s38, s39
	s_mul_hi_i32 s39, s38, 0x2e8ba2e9
	s_lshr_b32 s46, s39, 31
	s_ashr_i32 s39, s39, 5
	s_add_i32 s39, s39, s46
	s_lshl_b32 s46, s39, 2
	s_sub_i32 s47, 0x80, s46
	s_min_i32 s47, s47, 4
	s_mulk_i32 s39, 0xb0
	s_sub_i32 s38, s38, s39
	s_ashr_i32 s62, s38, 2
	s_mul_i32 s39, s62, s47
	s_sub_i32 s38, s38, s39
	s_add_i32 s66, s38, s46

;     __device__ bool map(long L, Unit& u) const {
;     ...
;         int wgid = (int)L; { const int q = nwg / NXCD, r = nwg % NXCD, xcd = wgid % NXCD, off = wgid / NXCD; wgid = (xcd < r ? xcd * (q + 1) : r * (q + 1) + (xcd - r) * q) + off; }
;         const int nig = WGM * nN, gid = wgid / nig, fm = gid * WGM, gsz = (nM - fm) < WGM ? (nM - fm) : WGM;
;         u.pm = fm + ((wgid % nig) % gsz); u.pn = (wgid % nig) / gsz; return true;
.LBB0_668:
	s_ashr_i32 s4, s22, 3
	s_add_i32 s4, s28, s4
	s_ashr_i32 s5, s4, 31
	s_lshr_b32 s5, s5, 27
	s_add_i32 s5, s4, s5
	s_ashr_i32 s22, s5, 5
	s_lshl_b32 s22, s22, 2
	s_sub_i32 s23, 0x80, s22
	s_min_i32 s23, s23, 4
	s_andn2_b32 s5, s5, 31
	s_sub_i32 s4, s4, s5
	s_ashr_i32 s56, s4, 2
	s_mul_i32 s5, s56, s23
	s_sub_i32 s4, s4, s5
	s_add_i32 s57, s22, s4
	s_mov_b32 s39, 0xb2a5705f
